# smp_ssd conv taps: all loads of an iteration in flight (tap-3 weights hoisted, bf16 unpack deferred); prologue transposer
# speedup vs baseline: 1.0036x; 1.0036x over previous
.LBB0_296:
	s_andn2_saveexec_b64 s[14:15], s[14:15]
	v_lshl_add_u32 v8, v73, 3, s69
	s_or_b64 exec, exec, s[14:15]
	v_ashrrev_i32_e32 v9, 31, v8
	v_lshlrev_b64 v[10:11], 2, v[8:9]
	v_lshl_add_u64 v[4:5], s[78:79], 0, v[10:11]
	global_load_dwordx4 v[0:3], v[4:5], off offset:16
	s_nop 0
	global_load_dwordx4 v[4:7], v[4:5], off
	s_movk_i32 s5, 0x11f
	v_cmp_lt_i32_e32 vcc, s5, v97
	s_and_saveexec_b64 s[14:15], vcc
	s_xor_b64 s[14:15], exec, s[14:15]
	s_cbranch_execz .LBB0_300
	v_add_u32_e32 v14, -3, v72
	v_mov_b64_e32 v[12:13], s[6:7]
	v_mad_u64_u32 v[12:13], s[28:29], v14, s54, v[12:13]
	v_lshl_add_u64 v[12:13], v[8:9], 1, v[12:13]
	v_add_co_u32_e32 v12, vcc, 0x2000, v12
	s_nop 1
	v_addc_co_u32_e32 v13, vcc, 0, v13, vcc
	global_load_dwordx4 v[16:19], v[12:13], off offset:2048
.LBB0_300:
	s_or_saveexec_b64 s[14:15], s[14:15]
	v_lshl_add_u64 v[66:67], s[8:9], 0, v[10:11]
	v_mul_lo_u32 v68, v72, s85
	s_xor_b64 exec, exec, s[14:15]
	s_cbranch_execz .LBB0_302
	v_ashrrev_i32_e32 v69, 31, v68
	v_lshl_add_u64 v[10:11], v[68:69], 2, v[66:67]
	global_load_dwordx4 v[12:15], v[10:11], off
	global_load_dwordx4 v[16:19], v[10:11], off offset:16
.LBB0_302:
	s_or_b64 exec, exec, s[14:15]
	v_lshl_add_u64 v[64:65], v[8:9], 2, s[92:93]
	global_load_dwordx4 v[20:23], v[64:65], off offset:16
	global_load_dwordx4 v[24:27], v[64:65], off
	s_movk_i32 s5, 0xbf
	v_cmp_lt_i32_e32 vcc, s5, v97
	s_and_saveexec_b64 s[14:15], vcc
	s_xor_b64 s[14:15], exec, s[14:15]
	s_cbranch_execz .LBB0_304
	v_add_u32_e32 v28, -2, v72
	v_mov_b64_e32 v[10:11], s[6:7]
	v_mad_u64_u32 v[10:11], s[28:29], v28, s54, v[10:11]
	v_lshl_add_u64 v[10:11], v[8:9], 1, v[10:11]
	v_add_co_u32_e32 v10, vcc, 0x2000, v10
	s_nop 1
	v_addc_co_u32_e32 v11, vcc, 0, v11, vcc
	global_load_dwordx4 v[32:35], v[10:11], off offset:2048
.LBB0_304:
	s_andn2_saveexec_b64 s[14:15], s[14:15]
	s_cbranch_execz .LBB0_306
	v_add_u32_e32 v10, 0x600, v68
	v_ashrrev_i32_e32 v11, 31, v10
	v_lshl_add_u64 v[10:11], v[10:11], 2, v[66:67]
	global_load_dwordx4 v[28:31], v[10:11], off
	global_load_dwordx4 v[32:35], v[10:11], off offset:16
.LBB0_306:
	s_or_b64 exec, exec, s[14:15]
	v_add_co_u32_e32 v36, vcc, 0x1000, v64
	v_lshl_add_u64 v[10:11], v[64:65], 0, s[34:35]
	s_nop 0
	v_addc_co_u32_e32 v37, vcc, 0, v65, vcc
	global_load_dwordx4 v[44:47], v[36:37], off offset:2048
	global_load_dwordx4 v[40:43], v[10:11], off offset:16
	s_movk_i32 s5, 0x5f
	v_cmp_lt_i32_e32 vcc, s5, v97
	s_and_saveexec_b64 s[14:15], vcc
	s_xor_b64 s[14:15], exec, s[14:15]
	s_cbranch_execz .LBB0_308
	v_add_u32_e32 v36, -1, v72
	v_mov_b64_e32 v[10:11], s[6:7]
	v_mad_u64_u32 v[10:11], s[28:29], v36, s54, v[10:11]
	v_lshl_add_u64 v[10:11], v[8:9], 1, v[10:11]
	v_add_co_u32_e32 v10, vcc, 0x2000, v10
	s_nop 1
	v_addc_co_u32_e32 v11, vcc, 0, v11, vcc
	global_load_dwordx4 v[36:39], v[10:11], off offset:2048
.LBB0_308:
	s_andn2_saveexec_b64 s[14:15], s[14:15]
	s_cbranch_execz .LBB0_310
	v_add_u32_e32 v10, 0xc00, v68
	v_ashrrev_i32_e32 v11, 31, v10
	v_lshl_add_u64 v[10:11], v[10:11], 2, v[66:67]
	global_load_dwordx4 v[48:51], v[10:11], off
	global_load_dwordx4 v[52:55], v[10:11], off offset:16
.LBB0_310:
	s_or_b64 exec, exec, s[14:15]
	v_add_co_u32_e32 v252, vcc, 0x3000, v64
	v_lshl_add_u64 v[10:11], v[64:65], 0, s[10:11]
	s_nop 0
	v_addc_co_u32_e32 v253, vcc, 0, v65, vcc
	global_load_dwordx4 v[60:63], v[252:253], off
	global_load_dwordx4 v[56:59], v[10:11], off offset:16
	s_movk_i32 s5, 0xffa0
	v_cmp_lt_i32_e32 vcc, s5, v97
	s_and_saveexec_b64 s[14:15], vcc
	s_xor_b64 s[14:15], exec, s[14:15]
	s_cbranch_execz .LBB0_312
	v_mov_b64_e32 v[10:11], s[6:7]
	v_mad_u64_u32 v[10:11], s[28:29], v72, s54, v[10:11]
	v_lshl_add_u64 v[8:9], v[8:9], 1, v[10:11]
	v_add_co_u32_e32 v8, vcc, 0x2000, v8
	s_nop 1
	v_addc_co_u32_e32 v9, vcc, 0, v9, vcc
	global_load_dwordx4 v[8:11], v[8:9], off offset:2048

.LBB0_314:
	s_or_b64 exec, exec, s[14:15]
	v_add_co_u32_e32 v252, vcc, s33, v64
	v_addc_co_u32_e32 v253, vcc, 0, v65, vcc
	v_lshl_add_u64 v[254:255], v[64:65], 0, s[76:77]
	global_load_dwordx4 v[244:247], v[252:253], off offset:2048
	global_load_dwordx4 v[248:251], v[254:255], off offset:16
	s_waitcnt vmcnt(0)
	v_cmp_lt_i32_e32 vcc, 0x11f, v97
	s_and_saveexec_b64 s[14:15], vcc
	v_lshlrev_b32_e32 v12, 16, v16
	v_and_b32_e32 v13, 0xffff0000, v16
	v_lshlrev_b32_e32 v14, 16, v17
	v_and_b32_e32 v15, 0xffff0000, v17
	v_lshlrev_b32_e32 v16, 16, v18
	v_and_b32_e32 v17, 0xffff0000, v18
	v_lshlrev_b32_e32 v18, 16, v19
	v_and_b32_e32 v19, 0xffff0000, v19
	s_or_b64 exec, exec, s[14:15]
	v_cmp_lt_i32_e32 vcc, 0xbf, v97
	s_and_saveexec_b64 s[14:15], vcc
	v_lshlrev_b32_e32 v28, 16, v32
	v_and_b32_e32 v29, 0xffff0000, v32
	v_lshlrev_b32_e32 v30, 16, v33
	v_and_b32_e32 v31, 0xffff0000, v33
	v_lshlrev_b32_e32 v32, 16, v34
	v_and_b32_e32 v33, 0xffff0000, v34
	v_lshlrev_b32_e32 v34, 16, v35
	v_and_b32_e32 v35, 0xffff0000, v35
	s_or_b64 exec, exec, s[14:15]
	v_cmp_lt_i32_e32 vcc, 0x5f, v97
	s_and_saveexec_b64 s[14:15], vcc
	v_lshlrev_b32_e32 v48, 16, v36
	v_and_b32_e32 v49, 0xffff0000, v36
	v_lshlrev_b32_e32 v50, 16, v37
	v_and_b32_e32 v51, 0xffff0000, v37
	v_lshlrev_b32_e32 v52, 16, v38
	v_and_b32_e32 v53, 0xffff0000, v38
	v_lshlrev_b32_e32 v54, 16, v39
	v_and_b32_e32 v55, 0xffff0000, v39
	s_or_b64 exec, exec, s[14:15]
	v_cmp_lt_i32_e32 vcc, 0xffffffa0, v97
	s_and_saveexec_b64 s[14:15], vcc
	v_lshlrev_b32_e32 v36, 16, v8
	v_and_b32_e32 v37, 0xffff0000, v8
	v_lshlrev_b32_e32 v38, 16, v9
	v_and_b32_e32 v39, 0xffff0000, v9
	v_lshlrev_b32_e32 v8, 16, v10
	v_and_b32_e32 v9, 0xffff0000, v10
	v_lshlrev_b32_e32 v10, 16, v11
	v_and_b32_e32 v11, 0xffff0000, v11
	s_or_b64 exec, exec, s[14:15]
	s_waitcnt vmcnt(4)
	v_pk_fma_f32 v[4:5], v[12:13], v[24:25], v[4:5]
	v_pk_fma_f32 v[0:1], v[16:17], v[20:21], v[0:1]
	s_waitcnt vmcnt(3)
	v_pk_fma_f32 v[4:5], v[28:29], v[44:45], v[4:5]
	s_waitcnt vmcnt(2)
	v_pk_fma_f32 v[0:1], v[32:33], v[40:41], v[0:1]
	v_pk_fma_f32 v[6:7], v[14:15], v[26:27], v[6:7]
	v_pk_fma_f32 v[2:3], v[18:19], v[22:23], v[2:3]
	s_waitcnt vmcnt(1)
	v_pk_fma_f32 v[16:17], v[48:49], v[60:61], v[4:5]
	s_waitcnt vmcnt(0)
	v_pk_fma_f32 v[4:5], v[52:53], v[56:57], v[0:1]
	v_pk_fma_f32 v[6:7], v[30:31], v[46:47], v[6:7]
	v_pk_fma_f32 v[2:3], v[34:35], v[42:43], v[2:3]
	v_pk_fma_f32 v[18:19], v[50:51], v[62:63], v[6:7]
	v_pk_fma_f32 v[6:7], v[54:55], v[58:59], v[2:3]
	s_nop 0
	s_waitcnt vmcnt(1)
	v_pk_fma_f32 v[0:1], v[36:37], v[244:245], v[16:17]
	s_waitcnt vmcnt(0)
	v_pk_fma_f32 v[4:5], v[8:9], v[248:249], v[4:5]
	v_mul_f32_e32 v16, 0xbfb8aa3b, v0
	v_mul_f32_e32 v17, 0xbfb8aa3b, v1
	v_mul_f32_e32 v8, 0xbfb8aa3b, v4
	v_mul_f32_e32 v9, 0xbfb8aa3b, v5
	v_exp_f32_e32 v16, v16
	v_exp_f32_e32 v17, v17
	v_exp_f32_e32 v8, v8
	v_exp_f32_e32 v9, v9
	v_add_f32_e32 v16, 1.0, v16
	v_add_f32_e32 v17, 1.0, v17
	v_add_f32_e32 v8, 1.0, v8
	v_add_f32_e32 v9, 1.0, v9
	v_rcp_f32_e32 v16, v16
	v_rcp_f32_e32 v17, v17
	v_rcp_f32_e32 v8, v8
	v_rcp_f32_e32 v9, v9
	v_pk_fma_f32 v[2:3], v[38:39], v[246:247], v[18:19]
	v_pk_fma_f32 v[6:7], v[10:11], v[250:251], v[6:7]
	v_pk_mul_f32 v[0:1], v[0:1], v[16:17]
	v_mul_f32_e32 v16, 0xbfb8aa3b, v2
	v_mul_f32_e32 v17, 0xbfb8aa3b, v3
	v_pk_mul_f32 v[4:5], v[4:5], v[8:9]
	v_mul_f32_e32 v8, 0xbfb8aa3b, v6
	v_mul_f32_e32 v9, 0xbfb8aa3b, v7
	v_exp_f32_e32 v16, v16
	v_exp_f32_e32 v17, v17
	v_exp_f32_e32 v8, v8
	v_exp_f32_e32 v9, v9
	v_add_f32_e32 v16, 1.0, v16
	v_add_f32_e32 v17, 1.0, v17
	v_add_f32_e32 v8, 1.0, v8
	v_add_f32_e32 v9, 1.0, v9
	v_rcp_f32_e32 v16, v16
	v_rcp_f32_e32 v17, v17
	v_rcp_f32_e32 v8, v8
	v_rcp_f32_e32 v9, v9
	v_pk_mul_f32 v[2:3], v[2:3], v[16:17]
	v_pk_mul_f32 v[6:7], v[6:7], v[8:9]
	s_and_saveexec_b64 s[14:15], s[2:3]
	s_xor_b64 s[2:3], exec, s[14:15]
	s_cbranch_execz .LBB0_320
	v_cmp_lt_u32_e32 vcc, s55, v73
	s_and_saveexec_b64 s[14:15], vcc
	s_xor_b64 s[14:15], exec, s[14:15]
	s_cbranch_execz .LBB0_317
	s_movk_i32 s5, 0x110
	v_cvt_pk_bf16_f32 v0, v0, v1
	v_cvt_pk_bf16_f32 v1, v2, v3
	v_cvt_pk_bf16_f32 v2, v4, v5
	v_mul_lo_u32 v4, v72, s5
	v_lshlrev_b32_e32 v5, 4, v73
	v_cvt_pk_bf16_f32 v3, v6, v7
	v_add3_u32 v4, 0, v4, v5
	ds_write_b128 v4, v[0:3] offset:39168

.LBB0_329:
	s_andn2_saveexec_b64 s[14:15], s[14:15]
	v_lshl_add_u32 v8, v74, 3, s69
	s_or_b64 exec, exec, s[14:15]
	v_ashrrev_i32_e32 v9, 31, v8
	v_lshlrev_b64 v[10:11], 2, v[8:9]
	v_lshl_add_u64 v[4:5], s[78:79], 0, v[10:11]
	global_load_dwordx4 v[0:3], v[4:5], off offset:16
	s_nop 0
	global_load_dwordx4 v[4:7], v[4:5], off
	s_movk_i32 s14, 0xff1f
	v_cmp_lt_i32_e32 vcc, s14, v97
	s_and_saveexec_b64 s[14:15], vcc
	s_xor_b64 s[14:15], exec, s[14:15]
	s_cbranch_execz .LBB0_333
	v_add_u32_e32 v14, -3, v73
	v_mov_b64_e32 v[12:13], s[6:7]
	v_mad_u64_u32 v[12:13], s[28:29], v14, s54, v[12:13]
	v_lshl_add_u64 v[12:13], v[8:9], 1, v[12:13]
	v_add_co_u32_e32 v12, vcc, 0x2000, v12
	s_nop 1
	v_addc_co_u32_e32 v13, vcc, 0, v13, vcc
	global_load_dwordx4 v[16:19], v[12:13], off offset:2048
.LBB0_333:
	s_or_saveexec_b64 s[14:15], s[14:15]
	v_lshl_add_u64 v[66:67], s[8:9], 0, v[10:11]
	v_mul_lo_u32 v68, v73, s85
	s_xor_b64 exec, exec, s[14:15]
	s_cbranch_execz .LBB0_335
	v_ashrrev_i32_e32 v69, 31, v68
	v_lshl_add_u64 v[10:11], v[68:69], 2, v[66:67]
	global_load_dwordx4 v[12:15], v[10:11], off
	global_load_dwordx4 v[16:19], v[10:11], off offset:16
.LBB0_335:
	s_or_b64 exec, exec, s[14:15]
	v_lshl_add_u64 v[64:65], v[8:9], 2, s[92:93]
	global_load_dwordx4 v[20:23], v[64:65], off offset:16
	global_load_dwordx4 v[24:27], v[64:65], off
	s_movk_i32 s8, 0xfebf
	v_cmp_lt_i32_e32 vcc, s8, v97
	s_and_saveexec_b64 s[8:9], vcc
	s_xor_b64 s[8:9], exec, s[8:9]
	s_cbranch_execz .LBB0_337
	v_add_u32_e32 v28, -2, v73
	v_mov_b64_e32 v[10:11], s[6:7]
	v_mad_u64_u32 v[10:11], s[14:15], v28, s54, v[10:11]
	v_lshl_add_u64 v[10:11], v[8:9], 1, v[10:11]
	v_add_co_u32_e32 v10, vcc, 0x2000, v10
	s_nop 1
	v_addc_co_u32_e32 v11, vcc, 0, v11, vcc
	global_load_dwordx4 v[32:35], v[10:11], off offset:2048
.LBB0_337:
	s_andn2_saveexec_b64 s[8:9], s[8:9]
	s_cbranch_execz .LBB0_339
	v_add_u32_e32 v10, 0x600, v68
	v_ashrrev_i32_e32 v11, 31, v10
	v_lshl_add_u64 v[10:11], v[10:11], 2, v[66:67]
	global_load_dwordx4 v[28:31], v[10:11], off
	global_load_dwordx4 v[32:35], v[10:11], off offset:16
.LBB0_339:
	s_or_b64 exec, exec, s[8:9]
	v_add_co_u32_e32 v36, vcc, 0x1000, v64
	v_lshl_add_u64 v[10:11], v[64:65], 0, s[34:35]
	s_nop 0
	v_addc_co_u32_e32 v37, vcc, 0, v65, vcc
	global_load_dwordx4 v[44:47], v[36:37], off offset:2048
	global_load_dwordx4 v[40:43], v[10:11], off offset:16
	s_movk_i32 s8, 0xfe5f
	v_cmp_lt_i32_e32 vcc, s8, v97
	s_and_saveexec_b64 s[8:9], vcc
	s_xor_b64 s[8:9], exec, s[8:9]
	s_cbranch_execz .LBB0_341
	v_add_u32_e32 v36, -1, v73
	v_mov_b64_e32 v[10:11], s[6:7]
	v_mad_u64_u32 v[10:11], s[14:15], v36, s54, v[10:11]
	v_lshl_add_u64 v[10:11], v[8:9], 1, v[10:11]
	v_add_co_u32_e32 v10, vcc, 0x2000, v10
	s_nop 1
	v_addc_co_u32_e32 v11, vcc, 0, v11, vcc
	global_load_dwordx4 v[36:39], v[10:11], off offset:2048
.LBB0_341:
	s_andn2_saveexec_b64 s[8:9], s[8:9]
	s_cbranch_execz .LBB0_343
	v_add_u32_e32 v10, 0xc00, v68
	v_ashrrev_i32_e32 v11, 31, v10
	v_lshl_add_u64 v[10:11], v[10:11], 2, v[66:67]
	global_load_dwordx4 v[48:51], v[10:11], off
	global_load_dwordx4 v[52:55], v[10:11], off offset:16
.LBB0_343:
	s_or_b64 exec, exec, s[8:9]
	v_add_co_u32_e32 v252, vcc, 0x3000, v64
	v_lshl_add_u64 v[10:11], v[64:65], 0, s[10:11]
	s_nop 0
	v_addc_co_u32_e32 v253, vcc, 0, v65, vcc
	global_load_dwordx4 v[60:63], v[252:253], off
	global_load_dwordx4 v[56:59], v[10:11], off offset:16
	s_movk_i32 s8, 0xfda0
	v_cmp_lt_i32_e32 vcc, s8, v97
	s_and_saveexec_b64 s[8:9], vcc
	s_xor_b64 s[8:9], exec, s[8:9]
	s_cbranch_execz .LBB0_345
	v_mov_b64_e32 v[10:11], s[6:7]
	v_mad_u64_u32 v[10:11], s[14:15], v73, s54, v[10:11]
	v_lshl_add_u64 v[8:9], v[8:9], 1, v[10:11]
	v_add_co_u32_e32 v8, vcc, 0x2000, v8
	s_nop 1
	v_addc_co_u32_e32 v9, vcc, 0, v9, vcc
	global_load_dwordx4 v[8:11], v[8:9], off offset:2048

.LBB0_347:
	s_or_b64 exec, exec, s[8:9]
	v_add_co_u32_e32 v252, vcc, s33, v64
	v_addc_co_u32_e32 v253, vcc, 0, v65, vcc
	v_lshl_add_u64 v[254:255], v[64:65], 0, s[76:77]
	global_load_dwordx4 v[244:247], v[252:253], off offset:2048
	global_load_dwordx4 v[248:251], v[254:255], off offset:16
	s_waitcnt vmcnt(0)
	v_cmp_lt_i32_e32 vcc, 0xffffff1f, v97
	s_and_saveexec_b64 s[14:15], vcc
	v_lshlrev_b32_e32 v12, 16, v16
	v_and_b32_e32 v13, 0xffff0000, v16
	v_lshlrev_b32_e32 v14, 16, v17
	v_and_b32_e32 v15, 0xffff0000, v17
	v_lshlrev_b32_e32 v16, 16, v18
	v_and_b32_e32 v17, 0xffff0000, v18
	v_lshlrev_b32_e32 v18, 16, v19
	v_and_b32_e32 v19, 0xffff0000, v19
	s_or_b64 exec, exec, s[14:15]
	v_cmp_lt_i32_e32 vcc, 0xfffffebf, v97
	s_and_saveexec_b64 s[14:15], vcc
	v_lshlrev_b32_e32 v28, 16, v32
	v_and_b32_e32 v29, 0xffff0000, v32
	v_lshlrev_b32_e32 v30, 16, v33
	v_and_b32_e32 v31, 0xffff0000, v33
	v_lshlrev_b32_e32 v32, 16, v34
	v_and_b32_e32 v33, 0xffff0000, v34
	v_lshlrev_b32_e32 v34, 16, v35
	v_and_b32_e32 v35, 0xffff0000, v35
	s_or_b64 exec, exec, s[14:15]
	v_cmp_lt_i32_e32 vcc, 0xfffffe5f, v97
	s_and_saveexec_b64 s[14:15], vcc
	v_lshlrev_b32_e32 v48, 16, v36
	v_and_b32_e32 v49, 0xffff0000, v36
	v_lshlrev_b32_e32 v50, 16, v37
	v_and_b32_e32 v51, 0xffff0000, v37
	v_lshlrev_b32_e32 v52, 16, v38
	v_and_b32_e32 v53, 0xffff0000, v38
	v_lshlrev_b32_e32 v54, 16, v39
	v_and_b32_e32 v55, 0xffff0000, v39
	s_or_b64 exec, exec, s[14:15]
	v_cmp_lt_i32_e32 vcc, 0xfffffda0, v97
	s_and_saveexec_b64 s[14:15], vcc
	v_lshlrev_b32_e32 v36, 16, v8
	v_and_b32_e32 v37, 0xffff0000, v8
	v_lshlrev_b32_e32 v38, 16, v9
	v_and_b32_e32 v39, 0xffff0000, v9
	v_lshlrev_b32_e32 v8, 16, v10
	v_and_b32_e32 v9, 0xffff0000, v10
	v_lshlrev_b32_e32 v10, 16, v11
	v_and_b32_e32 v11, 0xffff0000, v11
	s_or_b64 exec, exec, s[14:15]
	s_waitcnt vmcnt(4)
	v_pk_fma_f32 v[4:5], v[12:13], v[24:25], v[4:5]
	v_pk_fma_f32 v[0:1], v[16:17], v[20:21], v[0:1]
	s_waitcnt vmcnt(3)
	v_pk_fma_f32 v[4:5], v[28:29], v[44:45], v[4:5]
	s_waitcnt vmcnt(2)
	v_pk_fma_f32 v[0:1], v[32:33], v[40:41], v[0:1]
	v_pk_fma_f32 v[6:7], v[14:15], v[26:27], v[6:7]
	v_pk_fma_f32 v[2:3], v[18:19], v[22:23], v[2:3]
	s_waitcnt vmcnt(1)
	v_pk_fma_f32 v[16:17], v[48:49], v[60:61], v[4:5]
	s_waitcnt vmcnt(0)
	v_pk_fma_f32 v[4:5], v[52:53], v[56:57], v[0:1]
	v_pk_fma_f32 v[6:7], v[30:31], v[46:47], v[6:7]
	v_pk_fma_f32 v[2:3], v[34:35], v[42:43], v[2:3]
	v_pk_fma_f32 v[18:19], v[50:51], v[62:63], v[6:7]
	v_pk_fma_f32 v[6:7], v[54:55], v[58:59], v[2:3]
	s_nop 0
	s_waitcnt vmcnt(1)
	v_pk_fma_f32 v[0:1], v[36:37], v[244:245], v[16:17]
	s_waitcnt vmcnt(0)
	v_pk_fma_f32 v[4:5], v[8:9], v[248:249], v[4:5]
	v_mul_f32_e32 v16, 0xbfb8aa3b, v0
	v_mul_f32_e32 v17, 0xbfb8aa3b, v1
	v_mul_f32_e32 v8, 0xbfb8aa3b, v4
	v_mul_f32_e32 v9, 0xbfb8aa3b, v5
	v_exp_f32_e32 v16, v16
	v_exp_f32_e32 v17, v17
	v_exp_f32_e32 v8, v8
	v_exp_f32_e32 v9, v9
	v_add_f32_e32 v16, 1.0, v16
	v_add_f32_e32 v17, 1.0, v17
	v_add_f32_e32 v8, 1.0, v8
	v_add_f32_e32 v9, 1.0, v9
	v_rcp_f32_e32 v16, v16
	v_rcp_f32_e32 v17, v17
	v_rcp_f32_e32 v8, v8
	v_rcp_f32_e32 v9, v9
	v_pk_fma_f32 v[2:3], v[38:39], v[246:247], v[18:19]
	v_pk_fma_f32 v[6:7], v[10:11], v[250:251], v[6:7]
	v_pk_mul_f32 v[0:1], v[0:1], v[16:17]
	v_mul_f32_e32 v16, 0xbfb8aa3b, v2
	v_mul_f32_e32 v17, 0xbfb8aa3b, v3
	v_pk_mul_f32 v[4:5], v[4:5], v[8:9]
	v_mul_f32_e32 v8, 0xbfb8aa3b, v6
	v_mul_f32_e32 v9, 0xbfb8aa3b, v7
	v_exp_f32_e32 v16, v16
	v_exp_f32_e32 v17, v17
	v_exp_f32_e32 v8, v8
	v_exp_f32_e32 v9, v9
	v_add_f32_e32 v16, 1.0, v16
	v_add_f32_e32 v17, 1.0, v17
	v_add_f32_e32 v8, 1.0, v8
	v_add_f32_e32 v9, 1.0, v9
	v_rcp_f32_e32 v16, v16
	v_rcp_f32_e32 v17, v17
	v_rcp_f32_e32 v8, v8
	v_rcp_f32_e32 v9, v9
	v_pk_mul_f32 v[2:3], v[2:3], v[16:17]
	v_pk_mul_f32 v[6:7], v[6:7], v[8:9]
	s_and_saveexec_b64 s[8:9], s[2:3]
	s_xor_b64 s[2:3], exec, s[8:9]
	s_cbranch_execz .LBB0_353
	v_cmp_lt_u32_e32 vcc, s55, v74
	s_and_saveexec_b64 s[8:9], vcc
	s_xor_b64 s[8:9], exec, s[8:9]
	s_cbranch_execz .LBB0_350
	s_movk_i32 s14, 0x110
	v_cvt_pk_bf16_f32 v0, v0, v1
	v_cvt_pk_bf16_f32 v1, v2, v3
	v_cvt_pk_bf16_f32 v2, v4, v5
	v_mul_lo_u32 v4, v73, s14
	v_lshlrev_b32_e32 v5, 4, v74
	v_cvt_pk_bf16_f32 v3, v6, v7
	v_add3_u32 v4, 0, v4, v5
	ds_write_b128 v4, v[0:3] offset:39168
